# MLA: next-tile K fragment prefetch during PV plus DMA issue split between vector and matrix block
# baseline (speedup 1.0000x reference)
; #define KFRAG(da, dc, ks_) do { da = *(const LAS bf16x8*)(kb + r32 * KP + 16 * (ks_) + 8 * hf); dc = *(const LAS bf16x8*)(kb + (32 + r32) * KP + 16 * (ks_) + 8 * hf); } while (0)
; DI void mla_attn_phase(LAS unsigned char* lds, const bf16_t* Qg, const bf16_t* Kg, const bf16_t* Vtg, bf16_t* MIX) {
;     ...
;                     KFRAG(ka0, kc0_, 0); KFRAG(ka1, kc1_, 1);
.Lmla_nodma2:
	s_cmp_gt_i32 s40, s39
	s_cbranch_scc1 .LBB0_367
	s_waitcnt lgkmcnt(6)
	v_mfma_f32_32x32x16_bf16 v[64:79], v[144:147], v[80:83], v[64:79]
	v_mfma_f32_32x32x16_bf16 v[48:63], v[140:143], v[80:83], v[48:63]
	s_waitcnt lgkmcnt(0)
	v_mfma_f32_32x32x16_bf16 v[32:47], v[148:151], v[80:83], v[32:47]
	v_mfma_f32_32x32x16_bf16 v[16:31], v[152:155], v[80:83], v[16:31]
	ds_read_b128 v[80:83], v1 offset:13376
	ds_read_b128 v[96:99], v1 offset:17984
	ds_read_b128 v[100:103], v1 offset:22592
	ds_read_b128 v[104:107], v1 offset:27200
	v_mfma_f32_32x32x16_bf16 v[64:79], v[136:139], v[88:91], v[64:79]
	v_mfma_f32_32x32x16_bf16 v[48:63], v[12:15], v[88:91], v[48:63]
	v_mfma_f32_32x32x16_bf16 v[32:47], v[4:7], v[88:91], v[32:47]
	v_mfma_f32_32x32x16_bf16 v[16:31], v[8:11], v[88:91], v[16:31]
	ds_read_b128 v[4:7], v1 offset:13408
	ds_read_b128 v[8:11], v1 offset:18016
	ds_read_b128 v[12:15], v1 offset:22624
	ds_read_b128 v[88:91], v1 offset:27232
	s_add_i32 s30, s41, 1
	s_and_b32 s30, s30, 3
	s_lshl_b32 s30, s30, 15
	v_lshl_add_u32 v218, v166, 1, v230
	v_add_u32_e32 v218, s30, v218
	ds_read_b128 v[140:143], v218
	ds_read_b128 v[144:147], v218 offset:32
	ds_read_b128 v[148:151], v218 offset:6656
	ds_read_b128 v[152:155], v218 offset:6688
	s_waitcnt lgkmcnt(8)
	v_mfma_f32_32x32x16_bf16 v[64:79], v[80:83], v[84:87], v[64:79]
	v_mov_b32_e32 v233, v236
	v_mfma_f32_32x32x16_bf16 v[48:63], v[96:99], v[84:87], v[48:63]
	v_mfma_f32_32x32x16_bf16 v[32:47], v[100:103], v[84:87], v[32:47]
	v_mfma_f32_32x32x16_bf16 v[16:31], v[104:107], v[84:87], v[16:31]
	s_waitcnt lgkmcnt(4)
	v_mfma_f32_32x32x16_bf16 v[64:79], v[4:7], v[92:95], v[64:79]
	v_mfma_f32_32x32x16_bf16 v[48:63], v[8:11], v[92:95], v[48:63]
	v_mfma_f32_32x32x16_bf16 v[32:47], v[12:15], v[92:95], v[32:47]
	v_mfma_f32_32x32x16_bf16 v[16:31], v[88:91], v[92:95], v[16:31]
	s_branch .LBB0_371
